# ffnup k-loop rewritten: LDS-DMA staging + software-pipelined fragment reads (bf16 MFMA, f32 acc unchanged)
# speedup vs baseline: 1.0327x; 1.0327x over previous
; template <int MI, int NI>
; DI void gemm_kloop(const u16* Au, int lda, const u16* Bu, int ldb, int K, f32x4 (&acc)[NI][MI], unsigned char* smem) {
;   int tid_ = threadIdx.x; asm volatile("" : "+v"(tid_));
;   const int tid = tid_, lane = tid & 63, wave = tid >> 6, wm = wave >> 1, wn = wave & 1;
;   const int lr = tid >> 3, lc = tid & 7;
;   const int voa = lr * lda + lc * 8, vob = lr * ldb + lc * 8;
;   constexpr int NB2 = NI / 2;
;   u32x4 ra[MI], rb[NB2];
;   const int nk = K >> 6;
;   const int fsw = (lane & 15) >> 1;
;   const int fro0 = (lane & 15) * 128 + (((lane >> 4) ^ fsw) << 4);
;   const int fro1 = (lane & 15) * 128 + ((((lane >> 4) + 4) ^ fsw) << 4);
;   const int wof = lr * 128 + ((lc ^ ((lr >> 1) & 7)) << 4);
;     ...
;   GLOAD(0);
;   SWRITE(0);
; DI void phase_ffnup(const Params& p, int layer, unsigned char* smem) {
;     ...
;     const int g = it / (4 * NT), rem = it - g * (4 * NT), nt = rem >> 2, mt = g * 4 + (rem & 3);
;     const int b = mt / 17, ti = mt - b * 17, tbase = 254 * ti - 2;
;     f32x4 acc[8][4];
;     zero_acc<4, 8>(acc);
;     gemm_kloop<4, 8>(p.hb + ((ptrdiff_t)(b * TP + tbase)) * DM, DM, W + (size_t)(nt * 256) * DM, DM, DM, acc, smem);
.LBB0_23:
	s_mul_hi_i32 s2, s28, 0x2e8ba2e9
	s_lshr_b32 s3, s2, 31
	s_ashr_i32 s2, s2, 4
	s_add_i32 s53, s2, s3
	s_mul_i32 s2, s53, 0xffffffa8
	s_add_i32 s2, s2, s28
	s_ashr_i32 s34, s2, 2
	s_lshl_b32 s2, s53, 2
	s_and_b32 s3, s28, 3
	s_or_b32 s2, s2, s3
	s_mul_hi_i32 s3, s2, 0x78787879
	s_lshr_b32 s4, s3, 31
	s_ashr_i32 s3, s3, 3
	s_add_i32 s54, s3, s4
	s_mul_i32 s3, s54, 0xffffffef
	s_add_i32 s3, s3, s2
	s_mulk_i32 s3, 0xfe
	s_load_dwordx16 s[56:71], s[0:1], 0xc8
	s_add_i32 s35, s3, -2
	s_mul_i32 s2, s54, 0x1080
	v_mov_b32_e32 v52, v166
	s_add_i32 s4, s35, s2
	s_ashr_i32 s5, s4, 31
	v_lshlrev_b32_e32 v2, 3, v52
	v_ashrrev_i32_e32 v53, 3, v52
	v_and_b32_e32 v2, 56, v2
	s_and_b32 s52, s31, 3
	s_lshl_b64 s[4:5], s[4:5], 11
	v_lshl_or_b32 v2, v53, 10, v2
	s_waitcnt lgkmcnt(0)
	s_add_u32 s48, s56, s4
	v_ashrrev_i32_e32 v3, 31, v2
	s_addc_u32 s49, s57, s5
	s_waitcnt vmcnt(3)
	v_lshlrev_b64 v[34:35], 1, v[2:3]
	v_lshl_add_u64 v[36:37], s[48:49], 0, v[34:35]
	s_lshl_b32 s4, s34, 8
	s_waitcnt vmcnt(2)
	v_add_co_u32_e32 v38, vcc, s33, v36
	s_ashr_i32 s5, s4, 31
	s_nop 0
	v_addc_co_u32_e32 v39, vcc, 0, v37, vcc
	s_lshl_b64 s[4:5], s[4:5], 11
	v_add_co_u32_e32 v40, vcc, s36, v36
	s_add_u32 s50, s29, s4
	s_nop 0
	v_addc_co_u32_e32 v41, vcc, 0, v37, vcc
	s_addc_u32 s51, s30, s5
	s_waitcnt vmcnt(1)
	v_add_co_u32_e32 v42, vcc, s37, v36
	v_lshl_add_u64 v[44:45], s[50:51], 0, v[34:35]
	s_nop 0
	v_addc_co_u32_e32 v43, vcc, 0, v37, vcc
	s_waitcnt vmcnt(0)
	s_mov_b64 s[72:73], s[48:49]
	s_mov_b64 s[74:75], s[50:51]
	v_lshrrev_b32_e32 v190, 3, v166
	v_lshlrev_b32_e32 v191, 4, v166
	v_xor_b32_e32 v191, v191, v166
	v_and_b32_e32 v191, 0x70, v191
	v_lshl_or_b32 v186, v190, 11, v191
	v_add_u32_e32 v187, 0x20000, v186
	v_add_u32_e32 v188, 0x40000, v186
	v_add_u32_e32 v189, 0x60000, v186
	v_lshrrev_b32_e32 v192, 6, v166
	s_nop 0
	v_readfirstlane_b32 s88, v192
	v_and_b32_e32 v190, 15, v166
	v_bfe_u32 v191, v166, 4, 2
	v_lshrrev_b32_e32 v192, 1, v190
	v_xor_b32_e32 v230, v191, v192
	v_or_b32_e32 v191, 4, v191
	v_xor_b32_e32 v231, v191, v192
	v_lshlrev_b32_e32 v190, 7, v190
	v_lshl_or_b32 v230, v230, 4, v190
	v_lshl_or_b32 v231, v231, 4, v190
	v_lshrrev_b32_e32 v190, 7, v166
	v_bfe_u32 v191, v166, 6, 1
	v_mul_u32_u24_e32 v191, 0x4000, v191
	v_add_u32_e32 v232, v191, v230
	v_add_u32_e32 v233, v191, v231
	v_mul_u32_u24_e32 v190, 0x2000, v190
	v_add_u32_e32 v230, v190, v230
	v_add_u32_e32 v231, v190, v231
	s_lshl_b32 s88, s88, 10
	s_add_u32 s89, s88, 0x0
	s_mov_b32 m0, s89
	s_nop 0
	global_load_lds_dwordx4 v186, s[72:73]
	s_add_u32 m0, s89, 0x2000
	s_nop 0
	global_load_lds_dwordx4 v187, s[72:73]
	s_add_u32 m0, s89, 0x4000
	s_nop 0
	global_load_lds_dwordx4 v188, s[72:73]
	s_add_u32 m0, s89, 0x6000
	s_nop 0
	global_load_lds_dwordx4 v189, s[72:73]
	s_add_u32 m0, s89, 0x8000
	s_nop 0
	global_load_lds_dwordx4 v186, s[74:75]
	s_add_u32 m0, s89, 0xa000
	s_nop 0
	global_load_lds_dwordx4 v187, s[74:75]
	s_add_u32 m0, s89, 0xc000
	s_nop 0
	global_load_lds_dwordx4 v188, s[74:75]
	s_add_u32 m0, s89, 0xe000
	s_nop 0
	global_load_lds_dwordx4 v189, s[74:75]
	s_add_u32 s72, s72, 0x80
	s_addc_u32 s73, s73, 0
	s_add_u32 s74, s74, 0x80
	s_addc_u32 s75, s75, 0
	v_add_co_u32_e32 v46, vcc, s33, v44
	v_addc_co_u32_e32 v47, vcc, 0, v45, vcc
	v_add_co_u32_e32 v48, vcc, s36, v44
	v_addc_co_u32_e32 v49, vcc, 0, v45, vcc
	v_add_co_u32_e32 v50, vcc, s37, v44
	v_addc_co_u32_e32 v51, vcc, 0, v45, vcc
	s_add_u32 s4, s23, s4
	s_addc_u32 s5, s21, s5
	s_mulk_i32 s52, 0xfe
	v_lshl_add_u64 v[168:169], s[4:5], 0, v[34:35]
	s_mul_i32 s4, s53, 0x3f8
	s_add_i32 s4, s4, s52
	s_mulk_i32 s54, 0x5e
	s_sub_i32 s4, s4, s54
	v_lshlrev_b32_e32 v58, 4, v52
	s_add_i32 s4, s4, -2
	v_and_b32_e32 v54, 15, v52
	v_bfe_u32 v55, v52, 1, 3
	v_lshrrev_b32_e32 v56, 4, v52
	v_bfe_u32 v57, v52, 4, 2
	v_lshlrev_b32_e32 v59, 6, v52
	v_lshlrev_b32_e32 v60, 8, v52
	v_xor_b32_e32 v52, v58, v52
	v_lshlrev_b32_e32 v53, 7, v53
	s_ashr_i32 s5, s4, 31
	v_and_or_b32 v177, v52, s12, v53
	s_lshl_b64 s[4:5], s[4:5], 11
	v_lshlrev_b32_e32 v54, 7, v54
	v_bitop3_b32 v56, v56, v55, 3 bitop3:0x6c
	s_add_u32 s4, s56, s4
	v_lshl_or_b32 v176, v56, 4, v54
	s_addc_u32 s5, s57, s5
	s_mov_b32 s48, 0
	v_and_b32_e32 v174, 0xffffe000, v59
	v_and_b32_e32 v175, 0x4000, v60
	v_lshl_add_u64 v[170:171], s[4:5], 0, v[34:35]
	s_mov_b64 s[4:5], 0
	v_bitop3_b32 v2, v57, v55, 4 bitop3:0x36
	v_lshl_or_b32 v173, v2, 4, v54
	v_mov_b32_e32 v54, 0
	v_mov_b32_e32 v55, v54
	v_mov_b32_e32 v56, v54
	v_mov_b32_e32 v57, v54
	v_mov_b32_e32 v38, v54
	v_mov_b32_e32 v39, v54
	v_mov_b32_e32 v40, v54
	v_mov_b32_e32 v41, v54
	v_mov_b32_e32 v26, v54
	v_mov_b32_e32 v27, v54
	v_mov_b32_e32 v28, v54
	v_mov_b32_e32 v29, v54
	v_mov_b32_e32 v10, v54
	v_mov_b32_e32 v11, v54
	v_mov_b32_e32 v12, v54
	v_mov_b32_e32 v13, v54
	v_mov_b32_e32 v30, v54
	v_mov_b32_e32 v31, v54
	v_mov_b32_e32 v32, v54
	v_mov_b32_e32 v33, v54
	v_mov_b32_e32 v2, v54
	v_mov_b32_e32 v3, v54
	v_mov_b32_e32 v4, v54
	v_mov_b32_e32 v5, v54
	v_mov_b32_e32 v6, v54
	v_mov_b32_e32 v7, v54
	v_mov_b32_e32 v8, v54
	v_mov_b32_e32 v9, v54
	v_mov_b32_e32 v14, v54
	v_mov_b32_e32 v15, v54
	v_mov_b32_e32 v16, v54
	v_mov_b32_e32 v17, v54
	v_mov_b32_e32 v18, v54
	v_mov_b32_e32 v19, v54
	v_mov_b32_e32 v20, v54
	v_mov_b32_e32 v21, v54
	v_mov_b32_e32 v22, v54
	v_mov_b32_e32 v23, v54
	v_mov_b32_e32 v24, v54
	v_mov_b32_e32 v25, v54
	v_mov_b32_e32 v34, v54
	v_mov_b32_e32 v35, v54
	v_mov_b32_e32 v36, v54
	v_mov_b32_e32 v37, v54
	v_mov_b32_e32 v42, v54
	v_mov_b32_e32 v43, v54
	v_mov_b32_e32 v44, v54
	v_mov_b32_e32 v45, v54
	v_mov_b32_e32 v46, v54
	v_mov_b32_e32 v47, v54
	v_mov_b32_e32 v48, v54
	v_mov_b32_e32 v49, v54
	v_mov_b32_e32 v50, v54
; DI f32x4 mfma16(bf16x8 a, bf16x8 b, f32x4 c) { return __builtin_amdgcn_mfma_f32_16x16x32_bf16(a, b, c, 0, 0, 0); }
; template <int MI, int NI>
; DI void gemm_kloop(const u16* Au, int lda, const u16* Bu, int ldb, int K, f32x4 (&acc)[NI][MI], unsigned char* smem) {
;     ...
;   for (int kt = 0; kt < nk; ++kt) {
;     __syncthreads();
;     if (kt + 1 < nk) {
;       SWRITE((kt + 1) & 1);
;       if (kt + 2 < nk) GLOAD((kt + 2) << 6);
;     }
;     {
;       const unsigned char* sa = smem + (kt & 1) * 65536;
;       const unsigned char* sb = sa + 32768;
; #pragma unroll
;       for (int ks = 0; ks < 2; ++ks) {
;         const int fo = ks ? fro1 : fro0;
;         bf16x8 af[MI];
; #pragma unroll
;         for (int i = 0; i < MI; ++i) af[i] = *(const bf16x8*)(sa + (wm * 16 * MI + i * 16) * 128 + fo);
; #pragma unroll
;         for (int nh = 0; nh < NI; nh += 4) {
;           bf16x8 wf[4];
; #pragma unroll
;           for (int i = 0; i < 4; ++i) wf[i] = *(const bf16x8*)(sb + (wn * 16 * NI + (nh + i) * 16) * 128 + fo);
; #pragma unroll
;           for (int ni = 0; ni < 4; ++ni)
; #pragma unroll
;             for (int mi = 0; mi < MI; ++mi) acc[nh + ni][mi] = mfma16(wf[ni], af[mi], acc[nh + ni][mi]);
;         }
	v_mov_b32_e32 v51, v54
	v_mov_b32_e32 v52, v54
	v_mov_b32_e32 v53, v54
	v_mov_b32_e32 v58, v54
	v_mov_b32_e32 v59, v54
	v_mov_b32_e32 v60, v54
	v_mov_b32_e32 v61, v54
	v_mov_b32_e32 v62, v54
	v_mov_b32_e32 v63, v54
	v_mov_b32_e32 v64, v54
	v_mov_b32_e32 v65, v54
	v_mov_b32_e32 v66, v54
	v_mov_b32_e32 v67, v54
	v_mov_b32_e32 v68, v54
	v_mov_b32_e32 v69, v54
	v_mov_b32_e32 v70, v54
	v_mov_b32_e32 v71, v54
	v_mov_b32_e32 v72, v54
	v_mov_b32_e32 v73, v54
	v_mov_b32_e32 v74, v54
	v_mov_b32_e32 v75, v54
	v_mov_b32_e32 v76, v54
	v_mov_b32_e32 v77, v54
	v_mov_b32_e32 v78, v54
	v_mov_b32_e32 v79, v54
	v_mov_b32_e32 v80, v54
	v_mov_b32_e32 v81, v54
	v_mov_b32_e32 v82, v54
	v_mov_b32_e32 v83, v54
	v_mov_b32_e32 v84, v54
	v_mov_b32_e32 v85, v54
	v_mov_b32_e32 v86, v54
	v_mov_b32_e32 v87, v54
	v_mov_b32_e32 v88, v54
	v_mov_b32_e32 v89, v54
	v_mov_b32_e32 v90, v54
	v_mov_b32_e32 v91, v54
	v_mov_b32_e32 v92, v54
	v_mov_b32_e32 v93, v54
	v_mov_b32_e32 v94, v54
	v_mov_b32_e32 v95, v54
	v_mov_b32_e32 v96, v54
	v_mov_b32_e32 v97, v54
	v_mov_b32_e32 v98, v54
	v_mov_b32_e32 v99, v54
	v_mov_b32_e32 v100, v54
	v_mov_b32_e32 v101, v54
	v_mov_b32_e32 v102, v54
	v_mov_b32_e32 v103, v54
	v_mov_b32_e32 v104, v54
	v_mov_b32_e32 v105, v54
	v_mov_b32_e32 v106, v54
	v_mov_b32_e32 v107, v54
	v_mov_b32_e32 v108, v54
	v_mov_b32_e32 v109, v54
	v_mov_b32_e32 v114, v54
	v_mov_b32_e32 v115, v54
	v_mov_b32_e32 v116, v54
	v_mov_b32_e32 v117, v54
	v_mov_b32_e32 v146, v54
	v_mov_b32_e32 v147, v54
	v_mov_b32_e32 v148, v54
	v_mov_b32_e32 v149, v54
	v_mov_b32_e32 v154, v54
	v_mov_b32_e32 v155, v54
	v_mov_b32_e32 v156, v54
	v_mov_b32_e32 v157, v54
	v_mov_b32_e32 v150, v54
	v_mov_b32_e32 v151, v54
	v_mov_b32_e32 v152, v54
	v_mov_b32_e32 v153, v54
	v_mov_b32_e32 v158, v54
	v_mov_b32_e32 v159, v54
	v_mov_b32_e32 v160, v54
	v_mov_b32_e32 v161, v54
	s_mov_b32 s90, 0
	s_mov_b32 s91, 0x10000
.Lk_ffnup:
	s_waitcnt vmcnt(0) lgkmcnt(0)
	s_barrier
	ds_read_b128 v[118:121], v230
	ds_read_b128 v[122:125], v230 offset:2048
	ds_read_b128 v[130:133], v230 offset:4096
	ds_read_b128 v[134:137], v230 offset:6144
	ds_read_b128 v[110:113], v232 offset:32768
	ds_read_b128 v[126:129], v232 offset:34816
	ds_read_b128 v[162:165], v232 offset:36864
	s_add_u32 s89, s91, s88
	s_waitcnt lgkmcnt(2)
	v_mfma_f32_16x16x32_bf16 v[114:117], v[110:113], v[118:121], v[114:117]
	ds_read_b128 v[226:229], v232 offset:38912
	v_mfma_f32_16x16x32_bf16 v[106:109], v[110:113], v[122:125], v[106:109]
	v_mfma_f32_16x16x32_bf16 v[102:105], v[110:113], v[130:133], v[102:105]
	s_mov_b32 m0, s89
	s_nop 0
	global_load_lds_dwordx4 v186, s[72:73]
	v_mfma_f32_16x16x32_bf16 v[98:101], v[110:113], v[134:137], v[98:101]
	s_waitcnt lgkmcnt(2)
	v_mfma_f32_16x16x32_bf16 v[94:97], v[126:129], v[118:121], v[94:97]
	ds_read_b128 v[110:113], v232 offset:40960
	v_mfma_f32_16x16x32_bf16 v[90:93], v[126:129], v[122:125], v[90:93]
	ds_read_b128 v[138:141], v231
	v_mfma_f32_16x16x32_bf16 v[86:89], v[126:129], v[130:133], v[86:89]
	s_add_u32 m0, s89, 0x2000
	s_nop 0
	global_load_lds_dwordx4 v187, s[72:73]
	v_mfma_f32_16x16x32_bf16 v[82:85], v[126:129], v[134:137], v[82:85]
	s_waitcnt lgkmcnt(3)
	v_mfma_f32_16x16x32_bf16 v[78:81], v[162:165], v[118:121], v[78:81]
	ds_read_b128 v[126:129], v232 offset:43008
	v_mfma_f32_16x16x32_bf16 v[74:77], v[162:165], v[122:125], v[74:77]
	ds_read_b128 v[142:145], v231 offset:2048
	v_mfma_f32_16x16x32_bf16 v[70:73], v[162:165], v[130:133], v[70:73]
	s_add_u32 m0, s89, 0x4000
	s_nop 0
	global_load_lds_dwordx4 v188, s[72:73]
	v_mfma_f32_16x16x32_bf16 v[66:69], v[162:165], v[134:137], v[66:69]
	s_waitcnt lgkmcnt(4)
	v_mfma_f32_16x16x32_bf16 v[62:65], v[226:229], v[118:121], v[62:65]
	ds_read_b128 v[162:165], v232 offset:45056
	v_mfma_f32_16x16x32_bf16 v[58:61], v[226:229], v[122:125], v[58:61]
	ds_read_b128 v[178:181], v231 offset:4096
	v_mfma_f32_16x16x32_bf16 v[50:53], v[226:229], v[130:133], v[50:53]
	s_add_u32 m0, s89, 0x6000
	s_nop 0
	global_load_lds_dwordx4 v189, s[72:73]
	v_mfma_f32_16x16x32_bf16 v[46:49], v[226:229], v[134:137], v[46:49]
	s_waitcnt lgkmcnt(5)
	v_mfma_f32_16x16x32_bf16 v[42:45], v[110:113], v[118:121], v[42:45]
	ds_read_b128 v[226:229], v232 offset:47104
	v_mfma_f32_16x16x32_bf16 v[34:37], v[110:113], v[122:125], v[34:37]
	ds_read_b128 v[182:185], v231 offset:6144
	v_mfma_f32_16x16x32_bf16 v[22:25], v[110:113], v[130:133], v[22:25]
	s_add_u32 m0, s89, 0x8000
	s_nop 0
	global_load_lds_dwordx4 v186, s[74:75]
	v_mfma_f32_16x16x32_bf16 v[18:21], v[110:113], v[134:137], v[18:21]
	s_waitcnt lgkmcnt(5)
	v_mfma_f32_16x16x32_bf16 v[14:17], v[126:129], v[118:121], v[14:17]
	ds_read_b128 v[110:113], v233 offset:32768
	v_mfma_f32_16x16x32_bf16 v[6:9], v[126:129], v[122:125], v[6:9]
	v_mfma_f32_16x16x32_bf16 v[2:5], v[126:129], v[130:133], v[2:5]
	s_add_u32 m0, s89, 0xa000
	s_nop 0
	global_load_lds_dwordx4 v187, s[74:75]
	v_mfma_f32_16x16x32_bf16 v[30:33], v[126:129], v[134:137], v[30:33]
	s_waitcnt lgkmcnt(4)
	v_mfma_f32_16x16x32_bf16 v[10:13], v[162:165], v[118:121], v[10:13]
	ds_read_b128 v[126:129], v233 offset:34816
	v_mfma_f32_16x16x32_bf16 v[26:29], v[162:165], v[122:125], v[26:29]
	v_mfma_f32_16x16x32_bf16 v[38:41], v[162:165], v[130:133], v[38:41]
	s_add_u32 m0, s89, 0xc000
	s_nop 0
	global_load_lds_dwordx4 v188, s[74:75]
	v_mfma_f32_16x16x32_bf16 v[54:57], v[162:165], v[134:137], v[54:57]
	s_waitcnt lgkmcnt(3)
	v_mfma_f32_16x16x32_bf16 v[146:149], v[226:229], v[118:121], v[146:149]
	ds_read_b128 v[162:165], v233 offset:36864
	v_mfma_f32_16x16x32_bf16 v[154:157], v[226:229], v[122:125], v[154:157]
	v_mfma_f32_16x16x32_bf16 v[150:153], v[226:229], v[130:133], v[150:153]
	s_add_u32 m0, s89, 0xe000
	s_nop 0
	global_load_lds_dwordx4 v189, s[74:75]
	v_mfma_f32_16x16x32_bf16 v[158:161], v[226:229], v[134:137], v[158:161]
	s_waitcnt lgkmcnt(2)
; DI f32x4 mfma16(bf16x8 a, bf16x8 b, f32x4 c) { return __builtin_amdgcn_mfma_f32_16x16x32_bf16(a, b, c, 0, 0, 0); }
; template <int MI, int NI>
; DI void gemm_kloop(const u16* Au, int lda, const u16* Bu, int ldb, int K, f32x4 (&acc)[NI][MI], unsigned char* smem) {
;     ...
;   for (int kt = 0; kt < nk; ++kt) {
;     __syncthreads();
;     if (kt + 1 < nk) {
;       SWRITE((kt + 1) & 1);
;       if (kt + 2 < nk) GLOAD((kt + 2) << 6);
;     }
;     {
;       const unsigned char* sa = smem + (kt & 1) * 65536;
;       const unsigned char* sb = sa + 32768;
; #pragma unroll
;       for (int ks = 0; ks < 2; ++ks) {
;         const int fo = ks ? fro1 : fro0;
;         bf16x8 af[MI];
; #pragma unroll
;         for (int i = 0; i < MI; ++i) af[i] = *(const bf16x8*)(sa + (wm * 16 * MI + i * 16) * 128 + fo);
; #pragma unroll
;         for (int nh = 0; nh < NI; nh += 4) {
;           bf16x8 wf[4];
; #pragma unroll
;           for (int i = 0; i < 4; ++i) wf[i] = *(const bf16x8*)(sb + (wn * 16 * NI + (nh + i) * 16) * 128 + fo);
; #pragma unroll
;           for (int ni = 0; ni < 4; ++ni)
; #pragma unroll
;             for (int mi = 0; mi < MI; ++mi) acc[nh + ni][mi] = mfma16(wf[ni], af[mi], acc[nh + ni][mi]);
;         }
	v_mfma_f32_16x16x32_bf16 v[114:117], v[110:113], v[138:141], v[114:117]
	ds_read_b128 v[226:229], v233 offset:38912
	v_mfma_f32_16x16x32_bf16 v[106:109], v[110:113], v[142:145], v[106:109]
	v_mfma_f32_16x16x32_bf16 v[102:105], v[110:113], v[178:181], v[102:105]
	v_mfma_f32_16x16x32_bf16 v[98:101], v[110:113], v[182:185], v[98:101]
	s_waitcnt lgkmcnt(2)
	v_mfma_f32_16x16x32_bf16 v[94:97], v[126:129], v[138:141], v[94:97]
	ds_read_b128 v[110:113], v233 offset:40960
	v_mfma_f32_16x16x32_bf16 v[90:93], v[126:129], v[142:145], v[90:93]
	v_mfma_f32_16x16x32_bf16 v[86:89], v[126:129], v[178:181], v[86:89]
	v_mfma_f32_16x16x32_bf16 v[82:85], v[126:129], v[182:185], v[82:85]
	s_waitcnt lgkmcnt(2)
	v_mfma_f32_16x16x32_bf16 v[78:81], v[162:165], v[138:141], v[78:81]
	ds_read_b128 v[126:129], v233 offset:43008
	v_mfma_f32_16x16x32_bf16 v[74:77], v[162:165], v[142:145], v[74:77]
	v_mfma_f32_16x16x32_bf16 v[70:73], v[162:165], v[178:181], v[70:73]
	v_mfma_f32_16x16x32_bf16 v[66:69], v[162:165], v[182:185], v[66:69]
	s_waitcnt lgkmcnt(2)
	v_mfma_f32_16x16x32_bf16 v[62:65], v[226:229], v[138:141], v[62:65]
	ds_read_b128 v[162:165], v233 offset:45056
	v_mfma_f32_16x16x32_bf16 v[58:61], v[226:229], v[142:145], v[58:61]
	v_mfma_f32_16x16x32_bf16 v[50:53], v[226:229], v[178:181], v[50:53]
	v_mfma_f32_16x16x32_bf16 v[46:49], v[226:229], v[182:185], v[46:49]
	s_waitcnt lgkmcnt(2)
	v_mfma_f32_16x16x32_bf16 v[42:45], v[110:113], v[138:141], v[42:45]
	ds_read_b128 v[226:229], v233 offset:47104
	v_mfma_f32_16x16x32_bf16 v[34:37], v[110:113], v[142:145], v[34:37]
	v_mfma_f32_16x16x32_bf16 v[22:25], v[110:113], v[178:181], v[22:25]
	v_mfma_f32_16x16x32_bf16 v[18:21], v[110:113], v[182:185], v[18:21]
	s_waitcnt lgkmcnt(2)
	v_mfma_f32_16x16x32_bf16 v[14:17], v[126:129], v[138:141], v[14:17]
	v_mfma_f32_16x16x32_bf16 v[6:9], v[126:129], v[142:145], v[6:9]
	v_mfma_f32_16x16x32_bf16 v[2:5], v[126:129], v[178:181], v[2:5]
	v_mfma_f32_16x16x32_bf16 v[30:33], v[126:129], v[182:185], v[30:33]
	s_waitcnt lgkmcnt(1)
	v_mfma_f32_16x16x32_bf16 v[10:13], v[162:165], v[138:141], v[10:13]
	v_mfma_f32_16x16x32_bf16 v[26:29], v[162:165], v[142:145], v[26:29]
	v_mfma_f32_16x16x32_bf16 v[38:41], v[162:165], v[178:181], v[38:41]
	v_mfma_f32_16x16x32_bf16 v[54:57], v[162:165], v[182:185], v[54:57]
	s_waitcnt lgkmcnt(0)
	v_mfma_f32_16x16x32_bf16 v[146:149], v[226:229], v[138:141], v[146:149]
	v_mfma_f32_16x16x32_bf16 v[154:157], v[226:229], v[142:145], v[154:157]
	v_mfma_f32_16x16x32_bf16 v[150:153], v[226:229], v[178:181], v[150:153]
	v_mfma_f32_16x16x32_bf16 v[158:161], v[226:229], v[182:185], v[158:161]
	v_xor_b32_e32 v230, 0x10000, v230
	v_xor_b32_e32 v231, 0x10000, v231
	v_xor_b32_e32 v232, 0x10000, v232
	v_xor_b32_e32 v233, 0x10000, v233
	s_add_u32 s72, s72, 0x80
	s_addc_u32 s73, s73, 0
	s_add_u32 s74, s74, 0x80
	s_addc_u32 s75, s75, 0
	s_xor_b32 s91, s91, 0x10000
	s_add_u32 s90, s90, 1
	s_cmp_lg_u32 s90, 14
	s_cbranch_scc1 .Lk_ffnup
	s_waitcnt vmcnt(0)
	s_barrier
	s_add_u32 s89, s88, 0x10000
	s_mov_b32 m0, s89
	s_nop 0
	global_load_lds_dwordx4 v186, s[72:73]
	s_add_u32 m0, s89, 0x2000
	s_nop 0
	global_load_lds_dwordx4 v187, s[72:73]
	s_add_u32 m0, s89, 0x4000
	s_nop 0
	global_load_lds_dwordx4 v188, s[72:73]
	s_add_u32 m0, s89, 0x6000
	s_nop 0
	global_load_lds_dwordx4 v189, s[72:73]
	s_add_u32 m0, s89, 0x8000
	s_nop 0
	global_load_lds_dwordx4 v186, s[74:75]
	s_add_u32 m0, s89, 0xa000
	s_nop 0
	global_load_lds_dwordx4 v187, s[74:75]
	s_add_u32 m0, s89, 0xc000
	s_nop 0
	global_load_lds_dwordx4 v188, s[74:75]
	s_add_u32 m0, s89, 0xe000
	s_nop 0
	global_load_lds_dwordx4 v189, s[74:75]
	v_add_u32_e32 v138, v175, v176
	ds_read_b128 v[110:113], v138 offset:32768
	v_add_u32_e32 v134, v174, v176
	ds_read_b128 v[118:121], v134
	ds_read_b128 v[122:125], v134 offset:2048
	ds_read_b128 v[126:129], v138 offset:34816
	ds_read_b128 v[130:133], v134 offset:4096
	ds_read_b128 v[134:137], v134 offset:6144
	s_waitcnt lgkmcnt(4)
	v_mfma_f32_16x16x32_bf16 v[114:117], v[110:113], v[118:121], v[114:117]
	v_or_b32_e32 v186, 0x18000, v175
	v_add_u32_e32 v187, v186, v176
	v_add_u32_e32 v190, 0x10000, v174
	s_waitcnt lgkmcnt(3)
	v_mfma_f32_16x16x32_bf16 v[106:109], v[110:113], v[122:125], v[106:109]
	v_add_u32_e32 v194, v186, v173
	s_movk_i32 s4, 0x1080
	s_waitcnt lgkmcnt(1)
	v_mfma_f32_16x16x32_bf16 v[102:105], v[110:113], v[130:133], v[102:105]
	s_waitcnt lgkmcnt(0)
	v_mfma_f32_16x16x32_bf16 v[98:101], v[110:113], v[134:137], v[98:101]
	v_mfma_f32_16x16x32_bf16 v[94:97], v[126:129], v[118:121], v[94:97]
	v_mfma_f32_16x16x32_bf16 v[90:93], v[126:129], v[122:125], v[90:93]
	v_mfma_f32_16x16x32_bf16 v[86:89], v[126:129], v[130:133], v[86:89]
	v_mfma_f32_16x16x32_bf16 v[82:85], v[126:129], v[134:137], v[82:85]
	ds_read_b128 v[110:113], v138 offset:36864
	ds_read_b128 v[126:129], v138 offset:38912
	s_waitcnt lgkmcnt(1)
	v_mfma_f32_16x16x32_bf16 v[78:81], v[110:113], v[118:121], v[78:81]
	v_mfma_f32_16x16x32_bf16 v[74:77], v[110:113], v[122:125], v[74:77]
	v_mfma_f32_16x16x32_bf16 v[70:73], v[110:113], v[130:133], v[70:73]
	v_mfma_f32_16x16x32_bf16 v[66:69], v[110:113], v[134:137], v[66:69]
	s_waitcnt lgkmcnt(0)
	v_mfma_f32_16x16x32_bf16 v[62:65], v[126:129], v[118:121], v[62:65]
	v_mfma_f32_16x16x32_bf16 v[58:61], v[126:129], v[122:125], v[58:61]
	v_mfma_f32_16x16x32_bf16 v[50:53], v[126:129], v[130:133], v[50:53]
	v_mfma_f32_16x16x32_bf16 v[46:49], v[126:129], v[134:137], v[46:49]
	ds_read_b128 v[110:113], v138 offset:40960
	ds_read_b128 v[126:129], v138 offset:43008
	s_waitcnt lgkmcnt(1)
; DI f32x4 mfma16(bf16x8 a, bf16x8 b, f32x4 c) { return __builtin_amdgcn_mfma_f32_16x16x32_bf16(a, b, c, 0, 0, 0); }
; template <int MI, int NI>
; DI void gemm_kloop(const u16* Au, int lda, const u16* Bu, int ldb, int K, f32x4 (&acc)[NI][MI], unsigned char* smem) {
;     ...
;     {
;       const unsigned char* sa = smem + (kt & 1) * 65536;
;       const unsigned char* sb = sa + 32768;
; #pragma unroll
;       for (int ks = 0; ks < 2; ++ks) {
;         const int fo = ks ? fro1 : fro0;
;         bf16x8 af[MI];
; #pragma unroll
;         for (int i = 0; i < MI; ++i) af[i] = *(const bf16x8*)(sa + (wm * 16 * MI + i * 16) * 128 + fo);
; #pragma unroll
;         for (int nh = 0; nh < NI; nh += 4) {
;           bf16x8 wf[4];
; #pragma unroll
;           for (int i = 0; i < 4; ++i) wf[i] = *(const bf16x8*)(sb + (wn * 16 * NI + (nh + i) * 16) * 128 + fo);
; #pragma unroll
;           for (int ni = 0; ni < 4; ++ni)
; #pragma unroll
;             for (int mi = 0; mi < MI; ++mi) acc[nh + ni][mi] = mfma16(wf[ni], af[mi], acc[nh + ni][mi]);
;         }
	v_mfma_f32_16x16x32_bf16 v[42:45], v[110:113], v[118:121], v[42:45]
	v_mfma_f32_16x16x32_bf16 v[34:37], v[110:113], v[122:125], v[34:37]
	v_mfma_f32_16x16x32_bf16 v[22:25], v[110:113], v[130:133], v[22:25]
	v_mfma_f32_16x16x32_bf16 v[18:21], v[110:113], v[134:137], v[18:21]
	s_waitcnt lgkmcnt(0)
	v_mfma_f32_16x16x32_bf16 v[14:17], v[126:129], v[118:121], v[14:17]
	v_mfma_f32_16x16x32_bf16 v[6:9], v[126:129], v[122:125], v[6:9]
	v_mfma_f32_16x16x32_bf16 v[2:5], v[126:129], v[130:133], v[2:5]
	v_mfma_f32_16x16x32_bf16 v[30:33], v[126:129], v[134:137], v[30:33]
	ds_read_b128 v[110:113], v138 offset:45056
	ds_read_b128 v[126:129], v138 offset:47104
	s_waitcnt lgkmcnt(1)
	v_mfma_f32_16x16x32_bf16 v[10:13], v[110:113], v[118:121], v[10:13]
	v_mfma_f32_16x16x32_bf16 v[26:29], v[110:113], v[122:125], v[26:29]
	v_mfma_f32_16x16x32_bf16 v[38:41], v[110:113], v[130:133], v[38:41]
	v_mfma_f32_16x16x32_bf16 v[54:57], v[110:113], v[134:137], v[54:57]
	s_waitcnt lgkmcnt(0)
	v_mfma_f32_16x16x32_bf16 v[110:113], v[126:129], v[118:121], v[146:149]
	v_mfma_f32_16x16x32_bf16 v[118:121], v[126:129], v[122:125], v[154:157]
	s_nop 2
	v_add_u32_e32 v154, v175, v173
	v_mfma_f32_16x16x32_bf16 v[122:125], v[126:129], v[130:133], v[150:153]
	ds_read_b128 v[130:133], v154 offset:32768
	s_nop 1
	v_add_u32_e32 v150, v174, v173
	v_mfma_f32_16x16x32_bf16 v[126:129], v[126:129], v[134:137], v[158:161]
	ds_read_b128 v[134:137], v150
	ds_read_b128 v[138:141], v150 offset:2048
	ds_read_b128 v[142:145], v154 offset:34816
	ds_read_b128 v[146:149], v150 offset:4096
	ds_read_b128 v[150:153], v150 offset:6144
	s_waitcnt lgkmcnt(4)
	v_mfma_f32_16x16x32_bf16 v[114:117], v[130:133], v[134:137], v[114:117]
	s_waitcnt lgkmcnt(3)
	v_mfma_f32_16x16x32_bf16 v[106:109], v[130:133], v[138:141], v[106:109]
	s_waitcnt lgkmcnt(1)
	v_mfma_f32_16x16x32_bf16 v[102:105], v[130:133], v[146:149], v[102:105]
	s_waitcnt lgkmcnt(0)
	v_mfma_f32_16x16x32_bf16 v[98:101], v[130:133], v[150:153], v[98:101]
	v_mfma_f32_16x16x32_bf16 v[94:97], v[142:145], v[134:137], v[94:97]
	v_mfma_f32_16x16x32_bf16 v[90:93], v[142:145], v[138:141], v[90:93]
	v_mfma_f32_16x16x32_bf16 v[86:89], v[142:145], v[146:149], v[86:89]
	v_mfma_f32_16x16x32_bf16 v[82:85], v[142:145], v[150:153], v[82:85]
	ds_read_b128 v[130:133], v154 offset:36864
	ds_read_b128 v[142:145], v154 offset:38912
	s_waitcnt lgkmcnt(1)
	v_mfma_f32_16x16x32_bf16 v[78:81], v[130:133], v[134:137], v[78:81]
	v_mfma_f32_16x16x32_bf16 v[74:77], v[130:133], v[138:141], v[74:77]
	v_mfma_f32_16x16x32_bf16 v[70:73], v[130:133], v[146:149], v[70:73]
	v_mfma_f32_16x16x32_bf16 v[66:69], v[130:133], v[150:153], v[66:69]
	s_waitcnt lgkmcnt(0)
	v_mfma_f32_16x16x32_bf16 v[62:65], v[142:145], v[134:137], v[62:65]
	v_mfma_f32_16x16x32_bf16 v[58:61], v[142:145], v[138:141], v[58:61]
	v_mfma_f32_16x16x32_bf16 v[50:53], v[142:145], v[146:149], v[50:53]
	v_mfma_f32_16x16x32_bf16 v[46:49], v[142:145], v[150:153], v[46:49]
	ds_read_b128 v[130:133], v154 offset:40960
	ds_read_b128 v[142:145], v154 offset:43008
	s_waitcnt lgkmcnt(1)
	v_mfma_f32_16x16x32_bf16 v[42:45], v[130:133], v[134:137], v[42:45]
	v_mfma_f32_16x16x32_bf16 v[34:37], v[130:133], v[138:141], v[34:37]
	v_mfma_f32_16x16x32_bf16 v[22:25], v[130:133], v[146:149], v[22:25]
	v_mfma_f32_16x16x32_bf16 v[18:21], v[130:133], v[150:153], v[18:21]
	s_waitcnt lgkmcnt(0)
	v_mfma_f32_16x16x32_bf16 v[14:17], v[142:145], v[134:137], v[14:17]
	v_mfma_f32_16x16x32_bf16 v[6:9], v[142:145], v[138:141], v[6:9]
	v_mfma_f32_16x16x32_bf16 v[2:5], v[142:145], v[146:149], v[2:5]
	v_mfma_f32_16x16x32_bf16 v[30:33], v[142:145], v[150:153], v[30:33]
	ds_read_b128 v[130:133], v154 offset:45056
	ds_read_b128 v[142:145], v154 offset:47104
	s_waitcnt vmcnt(0) lgkmcnt(0)
	s_barrier
	v_mfma_f32_16x16x32_bf16 v[10:13], v[130:133], v[134:137], v[10:13]
	v_mfma_f32_16x16x32_bf16 v[26:29], v[130:133], v[138:141], v[26:29]
	v_mfma_f32_16x16x32_bf16 v[38:41], v[130:133], v[146:149], v[38:41]
	v_mfma_f32_16x16x32_bf16 v[54:57], v[130:133], v[150:153], v[54:57]
	ds_read_b128 v[130:133], v187
	v_mfma_f32_16x16x32_bf16 v[122:125], v[142:145], v[146:149], v[122:125]
	v_add_u32_e32 v146, v190, v176
	v_mfma_f32_16x16x32_bf16 v[110:113], v[142:145], v[134:137], v[110:113]
	ds_read_b128 v[134:137], v146
	v_mfma_f32_16x16x32_bf16 v[118:121], v[142:145], v[138:141], v[118:121]
	ds_read_b128 v[138:141], v146 offset:2048
	v_mfma_f32_16x16x32_bf16 v[126:129], v[142:145], v[150:153], v[126:129]
	ds_read_b128 v[142:145], v146 offset:4096
	ds_read_b128 v[146:149], v146 offset:6144
	s_waitcnt lgkmcnt(3)
	v_mfma_f32_16x16x32_bf16 v[114:117], v[130:133], v[134:137], v[114:117]
	s_waitcnt lgkmcnt(2)
	v_mfma_f32_16x16x32_bf16 v[106:109], v[130:133], v[138:141], v[106:109]
	s_waitcnt lgkmcnt(1)
	v_mfma_f32_16x16x32_bf16 v[102:105], v[130:133], v[142:145], v[102:105]
	s_waitcnt lgkmcnt(0)
	v_mfma_f32_16x16x32_bf16 v[98:101], v[130:133], v[146:149], v[98:101]
	ds_read_b128 v[130:133], v187 offset:2048
	s_waitcnt lgkmcnt(0)
	v_mfma_f32_16x16x32_bf16 v[94:97], v[130:133], v[134:137], v[94:97]
	v_mfma_f32_16x16x32_bf16 v[90:93], v[130:133], v[138:141], v[90:93]
	v_mfma_f32_16x16x32_bf16 v[86:89], v[130:133], v[142:145], v[86:89]
	v_mfma_f32_16x16x32_bf16 v[82:85], v[130:133], v[146:149], v[82:85]
	ds_read_b128 v[130:133], v187 offset:4096
	s_waitcnt lgkmcnt(0)
	v_mfma_f32_16x16x32_bf16 v[78:81], v[130:133], v[134:137], v[78:81]
	v_mfma_f32_16x16x32_bf16 v[74:77], v[130:133], v[138:141], v[74:77]
	v_mfma_f32_16x16x32_bf16 v[70:73], v[130:133], v[142:145], v[70:73]
	v_mfma_f32_16x16x32_bf16 v[66:69], v[130:133], v[146:149], v[66:69]
	ds_read_b128 v[130:133], v187 offset:6144
	s_waitcnt lgkmcnt(0)
; DI f32x4 mfma16(bf16x8 a, bf16x8 b, f32x4 c) { return __builtin_amdgcn_mfma_f32_16x16x32_bf16(a, b, c, 0, 0, 0); }
; template <int MI, int NI>
; DI void gemm_kloop(const u16* Au, int lda, const u16* Bu, int ldb, int K, f32x4 (&acc)[NI][MI], unsigned char* smem) {
;     ...
;     {
;       const unsigned char* sa = smem + (kt & 1) * 65536;
;       const unsigned char* sb = sa + 32768;
; #pragma unroll
;       for (int ks = 0; ks < 2; ++ks) {
;         const int fo = ks ? fro1 : fro0;
;         bf16x8 af[MI];
; #pragma unroll
;         for (int i = 0; i < MI; ++i) af[i] = *(const bf16x8*)(sa + (wm * 16 * MI + i * 16) * 128 + fo);
; #pragma unroll
;         for (int nh = 0; nh < NI; nh += 4) {
;           bf16x8 wf[4];
; #pragma unroll
;           for (int i = 0; i < 4; ++i) wf[i] = *(const bf16x8*)(sb + (wn * 16 * NI + (nh + i) * 16) * 128 + fo);
; #pragma unroll
;           for (int ni = 0; ni < 4; ++ni)
; #pragma unroll
;             for (int mi = 0; mi < MI; ++mi) acc[nh + ni][mi] = mfma16(wf[ni], af[mi], acc[nh + ni][mi]);
;         }
;       }
;     }
;   }
;   __syncthreads();
; DI void phase_ffnup(const Params& p, int layer, unsigned char* smem) {
;     ...
;     for (int mi = 0; mi < 4; ++mi) {
;       const int r = r0 + mi * 16;
;       tt[mi] = tbase + r;
;       float rs = (tt[mi] >= 0 && tt[mi] < TP) ? rsqrtf(rowss[b * TP + tt[mi]] * (1.f / DM) + EPS) : 0.f;
	v_mfma_f32_16x16x32_bf16 v[154:157], v[130:133], v[146:149], v[46:49]
	s_nop 2
	ds_read_b128 v[46:49], v187 offset:8192
	s_waitcnt lgkmcnt(0)
	v_mfma_f32_16x16x32_bf16 v[158:161], v[46:49], v[146:149], v[18:21]
	s_nop 2
	ds_read_b128 v[18:21], v187 offset:10240
	s_waitcnt lgkmcnt(0)
	v_mfma_f32_16x16x32_bf16 v[168:171], v[18:21], v[138:141], v[6:9]
	s_nop 2
	ds_read_b128 v[6:9], v187 offset:12288
	s_waitcnt lgkmcnt(0)
	v_mfma_f32_16x16x32_bf16 v[10:13], v[6:9], v[134:137], v[10:13]
	v_mfma_f32_16x16x32_bf16 v[174:177], v[6:9], v[138:141], v[26:29]
	v_mfma_f32_16x16x32_bf16 v[178:181], v[6:9], v[142:145], v[38:41]
	v_mfma_f32_16x16x32_bf16 v[182:185], v[6:9], v[146:149], v[54:57]
	ds_read_b128 v[6:9], v187 offset:14336
	s_nop 0
	ds_read_b128 v[38:41], v194
	v_mfma_f32_16x16x32_bf16 v[42:45], v[46:49], v[134:137], v[42:45]
	v_mfma_f32_16x16x32_bf16 v[34:37], v[46:49], v[138:141], v[34:37]
	v_mfma_f32_16x16x32_bf16 v[22:25], v[46:49], v[142:145], v[22:25]
	v_add_u32_e32 v46, v190, v173
	ds_read_b128 v[190:193], v46 offset:2048
	ds_read_b128 v[226:229], v46 offset:4096
	ds_read_b128 v[230:233], v46 offset:6144
	v_mfma_f32_16x16x32_bf16 v[30:33], v[18:21], v[146:149], v[30:33]
	s_waitcnt lgkmcnt(4)
	v_mfma_f32_16x16x32_bf16 v[126:129], v[6:9], v[146:149], v[126:129]
	ds_read_b128 v[146:149], v46
	v_mfma_f32_16x16x32_bf16 v[62:65], v[130:133], v[134:137], v[62:65]
	v_mfma_f32_16x16x32_bf16 v[150:153], v[130:133], v[138:141], v[58:61]
	v_mfma_f32_16x16x32_bf16 v[162:165], v[18:21], v[134:137], v[14:17]
	v_mfma_f32_16x16x32_bf16 v[2:5], v[18:21], v[142:145], v[2:5]
	v_mfma_f32_16x16x32_bf16 v[134:137], v[6:9], v[134:137], v[110:113]
	v_mfma_f32_16x16x32_bf16 v[138:141], v[6:9], v[138:141], v[118:121]
	v_mfma_f32_16x16x32_bf16 v[186:189], v[6:9], v[142:145], v[122:125]
	s_waitcnt lgkmcnt(0)
	v_mfma_f32_16x16x32_bf16 v[26:29], v[38:41], v[146:149], v[114:117]
	v_mfma_f32_16x16x32_bf16 v[18:21], v[38:41], v[190:193], v[106:109]
	v_mfma_f32_16x16x32_bf16 v[14:17], v[38:41], v[226:229], v[102:105]
	v_mfma_f32_16x16x32_bf16 v[6:9], v[38:41], v[230:233], v[98:101]
	ds_read_b128 v[38:41], v194 offset:2048
	v_mfma_f32_16x16x32_bf16 v[50:53], v[130:133], v[142:145], v[50:53]
	s_waitcnt lgkmcnt(0)
	v_mfma_f32_16x16x32_bf16 v[142:145], v[38:41], v[146:149], v[94:97]
	v_mfma_f32_16x16x32_bf16 v[130:133], v[38:41], v[190:193], v[90:93]
	v_mfma_f32_16x16x32_bf16 v[106:109], v[38:41], v[226:229], v[86:89]
	v_mfma_f32_16x16x32_bf16 v[98:101], v[38:41], v[230:233], v[82:85]
	ds_read_b128 v[38:41], v194 offset:4096
	s_waitcnt lgkmcnt(0)
	v_mfma_f32_16x16x32_bf16 v[58:61], v[38:41], v[146:149], v[78:81]
	v_mfma_f32_16x16x32_bf16 v[54:57], v[38:41], v[190:193], v[74:77]
	v_mfma_f32_16x16x32_bf16 v[46:49], v[38:41], v[226:229], v[70:73]
	v_mfma_f32_16x16x32_bf16 v[38:41], v[38:41], v[230:233], v[66:69]
	s_nop 2
	ds_read_b128 v[66:69], v194 offset:6144
	s_waitcnt lgkmcnt(0)
	v_mfma_f32_16x16x32_bf16 v[74:77], v[66:69], v[226:229], v[50:53]
	s_nop 2
	ds_read_b128 v[50:53], v194 offset:8192
	s_waitcnt lgkmcnt(0)
	v_mfma_f32_16x16x32_bf16 v[70:73], v[50:53], v[226:229], v[22:25]
	s_nop 2
	ds_read_b128 v[22:25], v194 offset:10240
	v_mfma_f32_16x16x32_bf16 v[86:89], v[50:53], v[146:149], v[42:45]
	s_waitcnt lgkmcnt(0)
	v_mfma_f32_16x16x32_bf16 v[42:45], v[22:25], v[226:229], v[2:5]
	s_nop 2
	ds_read_b128 v[2:5], v194 offset:12288
	s_waitcnt lgkmcnt(0)
	v_mfma_f32_16x16x32_bf16 v[122:125], v[2:5], v[146:149], v[10:13]
	v_mfma_f32_16x16x32_bf16 v[118:121], v[2:5], v[190:193], v[174:177]
	v_mfma_f32_16x16x32_bf16 v[102:105], v[2:5], v[226:229], v[178:181]
	v_mfma_f32_16x16x32_bf16 v[114:117], v[2:5], v[230:233], v[182:185]
	ds_read_b128 v[2:5], v194 offset:14336
	s_waitcnt lgkmcnt(0)
	s_barrier
	v_mfma_f32_16x16x32_bf16 v[94:97], v[66:69], v[146:149], v[62:65]
	v_mfma_f32_16x16x32_bf16 v[82:85], v[66:69], v[190:193], v[150:153]
	v_mfma_f32_16x16x32_bf16 v[66:69], v[66:69], v[230:233], v[154:157]
	s_nop 1
	v_mov_b32_e32 v152, 0
	v_mfma_f32_16x16x32_bf16 v[78:81], v[50:53], v[190:193], v[34:37]
	v_mov_b32_e32 v154, 0
	v_mfma_f32_16x16x32_bf16 v[110:113], v[50:53], v[230:233], v[158:161]
	v_mfma_f32_16x16x32_bf16 v[62:65], v[22:25], v[146:149], v[162:165]
	s_nop 1
	v_mov_b32_e32 v160, v0
	v_mfma_f32_16x16x32_bf16 v[50:53], v[22:25], v[190:193], v[168:171]
	v_mfma_f32_16x16x32_bf16 v[34:37], v[22:25], v[230:233], v[30:33]
	s_nop 1
	v_mov_b32_e32 v168, v172
	v_mfma_f32_16x16x32_bf16 v[30:33], v[2:5], v[146:149], v[134:137]
	v_add_u32_e32 v162, s35, v160
	v_cmp_gt_u32_e32 vcc, s4, v162
	v_mfma_f32_16x16x32_bf16 v[22:25], v[2:5], v[190:193], v[138:141]
	v_mfma_f32_16x16x32_bf16 v[10:13], v[2:5], v[226:229], v[186:189]
	v_mfma_f32_16x16x32_bf16 v[2:5], v[2:5], v[230:233], v[126:129]
	s_and_saveexec_b64 s[4:5], vcc
	s_cbranch_execz .LBB0_27
	s_ashr_i32 s35, s2, 31
	s_ashr_i32 s49, s3, 31
	s_add_u32 s48, s2, s3
	v_ashrrev_i32_e32 v161, 31, v160
	s_addc_u32 s49, s35, s49
	v_lshl_add_u64 v[90:91], s[48:49], 0, v[160:161]
	v_lshl_add_u64 v[90:91], v[90:91], 2, s[8:9]
	global_load_dword v90, v[90:91], off offset:-8
	s_waitcnt vmcnt(0)
	v_fmamk_f32 v90, v90, 0x3a800000, v199
	v_mul_f32_e32 v91, 0x4b800000, v90
	v_cmp_gt_f32_e32 vcc, s14, v90
	s_nop 1
	v_cndmask_b32_e32 v90, v90, v91, vcc
	v_rsq_f32_e32 v90, v90
	s_nop 0
	v_mul_f32_e32 v91, 0x45800000, v90
	v_cndmask_b32_e32 v154, v90, v91, vcc
